# MLA loop variant: a few softmax VALU ops ahead of the first MFMA of each tile (extended fast loop kept)
# baseline (speedup 1.0000x reference)
.Lmf_loop:
	ds_read_b128 v[162:165], v216 offset:13312
	ds_read_b128 v[166:169], v216 offset:19968
	ds_read_b128 v[172:175], v216 offset:13344
	ds_read_b128 v[176:179], v216 offset:20000
	ds_read_b128 v[180:183], v216 offset:13376
	global_load_dwordx4 v[130:133], v235, s[14:15]
	global_load_dwordx4 v[134:137], v236, s[14:15]
	s_add_u32 s14, s14, 0x18000
	s_addc_u32 s15, s15, 0
	global_load_dwordx4 v[142:145], v237, s[12:13]
	s_add_u32 s12, s12, 0x80
	s_addc_u32 s13, s13, 0
	v_exp_f32_e32 v66, v66
	v_exp_f32_e32 v67, v67
	v_exp_f32_e32 v68, v68
	v_exp_f32_e32 v69, v69
	v_add_f32_e32 v171, v66, v171
	s_waitcnt lgkmcnt(4)
	v_mfma_f32_32x32x16_bf16 v[34:49], v[162:165], v[98:101], v[146:161]
	ds_read_b128 v[184:187], v216 offset:20032
	v_exp_f32_e32 v70, v70
	v_exp_f32_e32 v71, v71
	v_add_f32_e32 v171, v68, v171
	v_exp_f32_e32 v72, v72
	s_waitcnt lgkmcnt(4)
	v_mfma_f32_32x32x16_bf16 v[50:65], v[166:169], v[98:101], v[146:161]
	ds_read_b128 v[188:191], v216 offset:13408
	v_add_f32_e32 v197, v67, v69
	v_exp_f32_e32 v73, v73
	v_add_f32_e32 v171, v70, v171
	v_add_f32_e32 v197, v71, v197
	v_cvt_pk_bf16_f32 v66, v66, v67
	s_waitcnt lgkmcnt(4)
	v_mfma_f32_32x32x16_bf16 v[34:49], v[172:175], v[102:105], v[34:49]
	ds_read_b128 v[192:195], v216 offset:20064
	v_add_f32_e32 v171, v72, v171
	v_cvt_pk_bf16_f32 v67, v68, v69
	v_add_f32_e32 v197, v73, v197
	v_cvt_pk_bf16_f32 v68, v70, v71
	v_cvt_pk_bf16_f32 v69, v72, v73
	v_exp_f32_e32 v74, v74
	s_waitcnt lgkmcnt(4)
	v_mfma_f32_32x32x16_bf16 v[50:65], v[176:179], v[102:105], v[50:65]
	ds_read_b128 v[162:165], v216 offset:13440
	v_exp_f32_e32 v75, v75
	v_exp_f32_e32 v76, v76
	v_exp_f32_e32 v77, v77
	s_waitcnt lgkmcnt(4)
	v_mfma_f32_32x32x16_bf16 v[34:49], v[180:183], v[106:109], v[34:49]
	ds_read_b128 v[166:169], v216 offset:20096
	v_add_f32_e32 v171, v74, v171
	v_exp_f32_e32 v78, v78
	v_add_f32_e32 v197, v75, v197
	v_exp_f32_e32 v79, v79
	s_waitcnt lgkmcnt(4)
	v_mfma_f32_32x32x16_bf16 v[50:65], v[184:187], v[106:109], v[50:65]
	ds_read_b128 v[172:175], v216 offset:13472
	v_add_f32_e32 v171, v76, v171
	v_exp_f32_e32 v80, v80
	v_add_f32_e32 v197, v77, v197
	v_exp_f32_e32 v81, v81
	s_waitcnt lgkmcnt(4)
	v_mfma_f32_32x32x16_bf16 v[34:49], v[188:191], v[110:113], v[34:49]
	ds_read_b128 v[176:179], v216 offset:20128
	v_add_f32_e32 v171, v78, v171
	v_add_f32_e32 v197, v79, v197
	v_cvt_pk_bf16_f32 v74, v74, v75
	v_add_f32_e32 v171, v80, v171
	v_cvt_pk_bf16_f32 v75, v76, v77
	s_waitcnt lgkmcnt(4)
	v_mfma_f32_32x32x16_bf16 v[50:65], v[192:195], v[110:113], v[50:65]
	ds_read_b128 v[180:183], v217 offset:26624
	v_add_f32_e32 v197, v81, v197
	v_cvt_pk_bf16_f32 v76, v78, v79
	v_cvt_pk_bf16_f32 v77, v80, v81
	v_exp_f32_e32 v82, v82
	v_exp_f32_e32 v83, v83
	s_waitcnt lgkmcnt(4)
	v_mfma_f32_32x32x16_bf16 v[34:49], v[162:165], v[114:117], v[34:49]
	ds_read_b128 v[184:187], v217 offset:31232
	v_exp_f32_e32 v84, v84
	v_exp_f32_e32 v85, v85
	v_add_f32_e32 v171, v82, v171
	v_exp_f32_e32 v86, v86
	s_waitcnt lgkmcnt(4)
	v_mfma_f32_32x32x16_bf16 v[50:65], v[166:169], v[114:117], v[50:65]
	ds_read_b128 v[188:191], v217 offset:26656
	v_add_f32_e32 v197, v83, v197
	v_exp_f32_e32 v87, v87
	v_add_f32_e32 v171, v84, v171
	v_exp_f32_e32 v88, v88
	s_waitcnt lgkmcnt(4)
	v_mfma_f32_32x32x16_bf16 v[34:49], v[172:175], v[118:121], v[34:49]
	ds_read_b128 v[192:195], v217 offset:31264
	v_add_f32_e32 v197, v85, v197
	v_exp_f32_e32 v89, v89
	v_add_f32_e32 v171, v86, v171
	v_add_f32_e32 v197, v87, v197
	s_waitcnt lgkmcnt(4)
	v_mfma_f32_32x32x16_bf16 v[50:65], v[176:179], v[118:121], v[50:65]
	ds_read_b128 v[162:165], v217 offset:26688
	v_cvt_pk_bf16_f32 v82, v82, v83
	v_add_f32_e32 v171, v88, v171
	v_cvt_pk_bf16_f32 v83, v84, v85
	v_add_f32_e32 v197, v89, v197
	v_cvt_pk_bf16_f32 v84, v86, v87
	v_cvt_pk_bf16_f32 v85, v88, v89
	s_waitcnt lgkmcnt(4)
	v_mfma_f32_32x32x16_bf16 v[18:33], v[180:183], v[66:69], v[18:33]
	ds_read_b128 v[166:169], v217 offset:31296
	v_exp_f32_e32 v90, v90
	v_exp_f32_e32 v91, v91
	v_exp_f32_e32 v92, v92
	s_waitcnt lgkmcnt(4)
	v_mfma_f32_32x32x16_bf16 v[2:17], v[184:187], v[66:69], v[2:17]
	ds_read_b128 v[172:175], v217 offset:26720
	v_exp_f32_e32 v93, v93
	v_add_f32_e32 v171, v90, v171
	v_exp_f32_e32 v94, v94
	v_add_f32_e32 v197, v91, v197
	s_waitcnt lgkmcnt(4)
	v_mfma_f32_32x32x16_bf16 v[18:33], v[188:191], v[74:77], v[18:33]
	ds_read_b128 v[176:179], v217 offset:31328
	v_exp_f32_e32 v95, v95
	v_add_f32_e32 v171, v92, v171
	v_exp_f32_e32 v96, v96
	v_add_f32_e32 v197, v93, v197
	s_waitcnt lgkmcnt(4)
	v_mfma_f32_32x32x16_bf16 v[2:17], v[192:195], v[74:77], v[2:17]
	s_waitcnt vmcnt(3)
	v_add_u32_e32 v196, 0x8800, v215
	ds_write_b128 v228, v[122:125]
	ds_write_b128 v238, v[126:129]
	ds_write2_b64 v196, v[138:139], v[140:141] offset0:128 offset1:130
	v_exp_f32_e32 v97, v97
	v_add_f32_e32 v171, v94, v171
	v_add_f32_e32 v197, v95, v197
	v_cvt_pk_bf16_f32 v90, v90, v91
	v_add_f32_e32 v171, v96, v171
	s_waitcnt lgkmcnt(6)
	v_mfma_f32_32x32x16_bf16 v[18:33], v[162:165], v[82:85], v[18:33]
	v_cvt_pk_bf16_f32 v91, v92, v93
	v_add_f32_e32 v197, v97, v197
	v_cvt_pk_bf16_f32 v92, v94, v95
	v_cvt_pk_bf16_f32 v93, v96, v97
	v_max3_f32 v1, v34, v35, v36
	v_max3_f32 v170, v37, v38, v39
	v_max3_f32 v1, v1, v40, v41
	s_waitcnt lgkmcnt(5)
	v_mfma_f32_32x32x16_bf16 v[2:17], v[166:169], v[82:85], v[2:17]
	v_max3_f32 v170, v170, v42, v43
	v_max3_f32 v1, v1, v44, v45
	v_max3_f32 v170, v170, v46, v47
	v_max3_f32 v1, v1, v48, v49
	v_max3_f32 v170, v170, v50, v51
	v_max3_f32 v1, v1, v52, v53
	s_waitcnt lgkmcnt(4)
	v_mfma_f32_32x32x16_bf16 v[18:33], v[172:175], v[90:93], v[18:33]
	v_max3_f32 v170, v170, v54, v55
	v_max3_f32 v1, v1, v56, v57
	v_max3_f32 v170, v170, v58, v59
	v_max3_f32 v1, v1, v60, v61
	v_max3_f32 v170, v170, v62, v63
	v_max3_f32 v1, v1, v64, v65
	s_waitcnt lgkmcnt(3)
	v_mfma_f32_32x32x16_bf16 v[2:17], v[176:179], v[90:93], v[2:17]
	v_max_f32_e32 v1, v1, v170
	v_mov_b32_e32 v170, v1
	v_add_f32_e32 v171, v197, v171
	s_nop 0
	v_permlane32_swap_b32_e32 v1, v170
	v_max_f32_e32 v1, v1, v170
	v_cmp_lt_f32_e32 vcc, s93, v1
	s_cbranch_vccnz .Lmf_slow_0
.Lmf_join_0:
	s_waitcnt lgkmcnt(0)
	s_barrier
	ds_read_b128 v[162:165], v216 offset:0
	ds_read_b128 v[166:169], v216 offset:6656
	ds_read_b128 v[172:175], v216 offset:32
	ds_read_b128 v[176:179], v216 offset:6688
	ds_read_b128 v[180:183], v216 offset:64
	global_load_dwordx4 v[122:125], v235, s[14:15]
	global_load_dwordx4 v[126:129], v236, s[14:15]
	s_add_u32 s14, s14, 0x18000
	s_addc_u32 s15, s15, 0
	global_load_dwordx4 v[138:141], v237, s[12:13]
	s_add_u32 s12, s12, 0x80
	s_addc_u32 s13, s13, 0
	v_exp_f32_e32 v34, v34
	v_exp_f32_e32 v35, v35
	v_exp_f32_e32 v36, v36
	v_exp_f32_e32 v37, v37
	v_add_f32_e32 v171, v34, v171
	s_waitcnt lgkmcnt(4)
	v_mfma_f32_32x32x16_bf16 v[66:81], v[162:165], v[98:101], v[146:161]
	ds_read_b128 v[184:187], v216 offset:6720
	v_exp_f32_e32 v38, v38
	v_exp_f32_e32 v39, v39
	v_add_f32_e32 v171, v36, v171
	v_exp_f32_e32 v40, v40
	s_waitcnt lgkmcnt(4)
	v_mfma_f32_32x32x16_bf16 v[82:97], v[166:169], v[98:101], v[146:161]
	ds_read_b128 v[188:191], v216 offset:96
	v_add_f32_e32 v197, v35, v37
	v_exp_f32_e32 v41, v41
	v_add_f32_e32 v171, v38, v171
	v_add_f32_e32 v197, v39, v197
	v_cvt_pk_bf16_f32 v34, v34, v35
	s_waitcnt lgkmcnt(4)
	v_mfma_f32_32x32x16_bf16 v[66:81], v[172:175], v[102:105], v[66:81]
	ds_read_b128 v[192:195], v216 offset:6752
	v_add_f32_e32 v171, v40, v171
	v_cvt_pk_bf16_f32 v35, v36, v37
	v_add_f32_e32 v197, v41, v197
	v_cvt_pk_bf16_f32 v36, v38, v39
	v_cvt_pk_bf16_f32 v37, v40, v41
	v_exp_f32_e32 v42, v42
	s_waitcnt lgkmcnt(4)
	v_mfma_f32_32x32x16_bf16 v[82:97], v[176:179], v[102:105], v[82:97]
	ds_read_b128 v[162:165], v216 offset:128
	v_exp_f32_e32 v43, v43
	v_exp_f32_e32 v44, v44
	v_exp_f32_e32 v45, v45
	s_waitcnt lgkmcnt(4)
	v_mfma_f32_32x32x16_bf16 v[66:81], v[180:183], v[106:109], v[66:81]
	ds_read_b128 v[166:169], v216 offset:6784
	v_add_f32_e32 v171, v42, v171
	v_exp_f32_e32 v46, v46
	v_add_f32_e32 v197, v43, v197
	v_exp_f32_e32 v47, v47
	s_waitcnt lgkmcnt(4)
	v_mfma_f32_32x32x16_bf16 v[82:97], v[184:187], v[106:109], v[82:97]
	ds_read_b128 v[172:175], v216 offset:160
	v_add_f32_e32 v171, v44, v171
	v_exp_f32_e32 v48, v48
	v_add_f32_e32 v197, v45, v197
	v_exp_f32_e32 v49, v49
	s_waitcnt lgkmcnt(4)
	v_mfma_f32_32x32x16_bf16 v[66:81], v[188:191], v[110:113], v[66:81]
	ds_read_b128 v[176:179], v216 offset:6816
	v_add_f32_e32 v171, v46, v171
	v_add_f32_e32 v197, v47, v197
	v_cvt_pk_bf16_f32 v42, v42, v43
	v_add_f32_e32 v171, v48, v171
	v_cvt_pk_bf16_f32 v43, v44, v45
	s_waitcnt lgkmcnt(4)
	v_mfma_f32_32x32x16_bf16 v[82:97], v[192:195], v[110:113], v[82:97]
	ds_read_b128 v[180:183], v217 offset:35840
	v_add_f32_e32 v197, v49, v197
	v_cvt_pk_bf16_f32 v44, v46, v47
	v_cvt_pk_bf16_f32 v45, v48, v49
	v_exp_f32_e32 v50, v50
	v_exp_f32_e32 v51, v51
	s_waitcnt lgkmcnt(4)
	v_mfma_f32_32x32x16_bf16 v[66:81], v[162:165], v[114:117], v[66:81]
	ds_read_b128 v[184:187], v217 offset:40448
	v_exp_f32_e32 v52, v52
	v_exp_f32_e32 v53, v53
	v_add_f32_e32 v171, v50, v171
	v_exp_f32_e32 v54, v54
	s_waitcnt lgkmcnt(4)
	v_mfma_f32_32x32x16_bf16 v[82:97], v[166:169], v[114:117], v[82:97]
	ds_read_b128 v[188:191], v217 offset:35872
	v_add_f32_e32 v197, v51, v197
	v_exp_f32_e32 v55, v55
	v_add_f32_e32 v171, v52, v171
	v_exp_f32_e32 v56, v56
	s_waitcnt lgkmcnt(4)
	v_mfma_f32_32x32x16_bf16 v[66:81], v[172:175], v[118:121], v[66:81]
	ds_read_b128 v[192:195], v217 offset:40480
	v_add_f32_e32 v197, v53, v197
	v_exp_f32_e32 v57, v57
	v_add_f32_e32 v171, v54, v171
	v_add_f32_e32 v197, v55, v197
	s_waitcnt lgkmcnt(4)
	v_mfma_f32_32x32x16_bf16 v[82:97], v[176:179], v[118:121], v[82:97]
	ds_read_b128 v[162:165], v217 offset:35904
	v_cvt_pk_bf16_f32 v50, v50, v51
	v_add_f32_e32 v171, v56, v171
	v_cvt_pk_bf16_f32 v51, v52, v53
	v_add_f32_e32 v197, v57, v197
	v_cvt_pk_bf16_f32 v52, v54, v55
	v_cvt_pk_bf16_f32 v53, v56, v57
	s_waitcnt lgkmcnt(4)
	v_mfma_f32_32x32x16_bf16 v[18:33], v[180:183], v[34:37], v[18:33]
	ds_read_b128 v[166:169], v217 offset:40512
	v_exp_f32_e32 v58, v58
	v_exp_f32_e32 v59, v59
	v_exp_f32_e32 v60, v60
	s_waitcnt lgkmcnt(4)
	v_mfma_f32_32x32x16_bf16 v[2:17], v[184:187], v[34:37], v[2:17]
	ds_read_b128 v[172:175], v217 offset:35936
	v_exp_f32_e32 v61, v61
	v_add_f32_e32 v171, v58, v171
	v_exp_f32_e32 v62, v62
	v_add_f32_e32 v197, v59, v197
	s_waitcnt lgkmcnt(4)
	v_mfma_f32_32x32x16_bf16 v[18:33], v[188:191], v[42:45], v[18:33]
	ds_read_b128 v[176:179], v217 offset:40544
	v_exp_f32_e32 v63, v63
	v_add_f32_e32 v171, v60, v171
	v_exp_f32_e32 v64, v64
	v_add_f32_e32 v197, v61, v197
	s_waitcnt lgkmcnt(4)
	v_mfma_f32_32x32x16_bf16 v[2:17], v[192:195], v[42:45], v[2:17]
	s_waitcnt vmcnt(3)
	ds_write_b128 v228, v[130:133] offset:13312
	ds_write_b128 v238, v[134:137] offset:13312
	ds_write2_b64 v225, v[142:143], v[144:145] offset1:2
	v_exp_f32_e32 v65, v65
	v_add_f32_e32 v171, v62, v171
	v_add_f32_e32 v197, v63, v197
	v_cvt_pk_bf16_f32 v58, v58, v59
	v_add_f32_e32 v171, v64, v171
	s_waitcnt lgkmcnt(6)
	v_mfma_f32_32x32x16_bf16 v[18:33], v[162:165], v[50:53], v[18:33]
	v_cvt_pk_bf16_f32 v59, v60, v61
	v_add_f32_e32 v197, v65, v197
	v_cvt_pk_bf16_f32 v60, v62, v63
	v_cvt_pk_bf16_f32 v61, v64, v65
	v_max3_f32 v1, v66, v67, v68
	v_max3_f32 v170, v69, v70, v71
	v_max3_f32 v1, v1, v72, v73
	s_waitcnt lgkmcnt(5)
	v_mfma_f32_32x32x16_bf16 v[2:17], v[166:169], v[50:53], v[2:17]
	v_max3_f32 v170, v170, v74, v75
	v_max3_f32 v1, v1, v76, v77
	v_max3_f32 v170, v170, v78, v79
	v_max3_f32 v1, v1, v80, v81
	v_max3_f32 v170, v170, v82, v83
	v_max3_f32 v1, v1, v84, v85
	s_waitcnt lgkmcnt(4)
	v_mfma_f32_32x32x16_bf16 v[18:33], v[172:175], v[58:61], v[18:33]
	v_max3_f32 v170, v170, v86, v87
	v_max3_f32 v1, v1, v88, v89
	v_max3_f32 v170, v170, v90, v91
	v_max3_f32 v1, v1, v92, v93
	v_max3_f32 v170, v170, v94, v95
	v_max3_f32 v1, v1, v96, v97
	s_waitcnt lgkmcnt(3)
	v_mfma_f32_32x32x16_bf16 v[2:17], v[176:179], v[58:61], v[2:17]
	v_max_f32_e32 v1, v1, v170
	v_mov_b32_e32 v170, v1
	v_add_f32_e32 v171, v197, v171
	s_nop 0
	v_permlane32_swap_b32_e32 v1, v170
	v_max_f32_e32 v1, v1, v170
	v_cmp_lt_f32_e32 vcc, s93, v1
	s_cbranch_vccnz .Lmf_slow_1
